# S7 epilogue: per-group counted waits for the first bf16 residual batch (vmcnt 14/12/18/20)
# baseline (speedup 1.0000x reference)
.LBB0_1487:
	v_lshl_add_u32 v148, s35, 8, v152
	v_lshl_add_u32 v144, s36, 8, v154
	v_ashrrev_i32_e32 v145, 31, v144
	v_ashrrev_i32_e32 v149, 31, v148
	v_lshl_add_u64 v[146:147], v[144:145], 1, s[8:9]
	v_lshlrev_b64 v[150:151], 12, v[148:149]
	v_or_b32_e32 v182, 16, v148
	v_lshl_add_u64 v[150:151], v[146:147], 0, v[150:151]
	v_ashrrev_i32_e32 v183, 31, v182
	global_load_dwordx4 v[158:161], v[150:151], off
	global_load_dwordx4 v[162:165], v[150:151], off offset:256
	v_lshlrev_b64 v[150:151], 12, v[182:183]
	v_or_b32_e32 v190, 32, v148
	v_lshl_add_u64 v[150:151], v[146:147], 0, v[150:151]
	v_ashrrev_i32_e32 v191, 31, v190
	global_load_dwordx4 v[166:169], v[150:151], off
	global_load_dwordx4 v[170:173], v[150:151], off offset:256
	v_lshlrev_b64 v[150:151], 12, v[190:191]
	v_lshl_add_u64 v[178:179], v[146:147], 0, v[150:151]
	global_load_dwordx4 v[174:177], v[178:179], off
	v_or_b32_e32 v150, 48, v148
	global_load_dwordx4 v[178:181], v[178:179], off offset:256
	v_ashrrev_i32_e32 v151, 31, v150
	v_lshlrev_b64 v[186:187], 12, v[150:151]
	v_lshl_add_u64 v[144:145], v[144:145], 2, s[52:53]
	v_lshlrev_b64 v[184:185], 13, v[148:149]
	v_lshlrev_b64 v[182:183], 13, v[182:183]
	v_lshl_add_u64 v[186:187], v[146:147], 0, v[186:187]
	v_lshl_add_u64 v[192:193], v[144:145], 0, v[184:185]
	v_lshl_add_u64 v[194:195], v[144:145], 0, v[182:183]
	global_load_dwordx4 v[182:185], v[186:187], off
	s_nop 0
	global_load_dwordx4 v[186:189], v[186:187], off offset:256
	v_add_u32_e32 v210, 0x80, v148
	v_ashrrev_i32_e32 v211, 31, v210
	v_lshlrev_b64 v[208:209], 12, v[210:211]
	v_lshl_add_u64 v[208:209], v[146:147], 0, v[208:209]
	global_load_dwordx4 v[224:227], v[208:209], off
	global_load_dwordx4 v[228:231], v[208:209], off offset:256
	v_add_u32_e32 v210, 0x90, v148
	v_ashrrev_i32_e32 v211, 31, v210
	v_lshlrev_b64 v[208:209], 12, v[210:211]
	v_lshl_add_u64 v[208:209], v[146:147], 0, v[208:209]
	global_load_dwordx4 v[232:235], v[208:209], off
	global_load_dwordx4 v[236:239], v[208:209], off offset:256
	v_add_u32_e32 v210, 0xa0, v148
	v_ashrrev_i32_e32 v211, 31, v210
	v_lshlrev_b64 v[208:209], 12, v[210:211]
	v_lshl_add_u64 v[208:209], v[146:147], 0, v[208:209]
	global_load_dwordx4 v[240:243], v[208:209], off
	global_load_dwordx4 v[244:247], v[208:209], off offset:256
	v_add_u32_e32 v210, 0xb0, v148
	v_ashrrev_i32_e32 v211, 31, v210
	v_lshlrev_b64 v[208:209], 12, v[210:211]
	v_lshl_add_u64 v[208:209], v[146:147], 0, v[208:209]
	global_load_dwordx4 v[248:251], v[208:209], off
	global_load_dwordx4 v[204:207], v[208:209], off offset:256
	s_and_b64 vcc, exec, s[6:7]
	s_mov_b64 s[6:7], -1
	s_waitcnt vmcnt(14) lgkmcnt(0)
	v_lshlrev_b32_e32 v196, 16, v158
	v_and_b32_e32 v197, 0xffff0000, v158
	v_lshlrev_b32_e32 v158, 16, v159
	v_and_b32_e32 v159, 0xffff0000, v159
	v_lshlrev_b32_e32 v198, 16, v160
	v_and_b32_e32 v199, 0xffff0000, v160
	v_lshlrev_b32_e32 v160, 16, v161
	v_and_b32_e32 v161, 0xffff0000, v161
	v_lshlrev_b32_e32 v200, 16, v162
	v_and_b32_e32 v201, 0xffff0000, v162
	v_lshlrev_b32_e32 v162, 16, v163
	v_and_b32_e32 v163, 0xffff0000, v163
	v_lshlrev_b32_e32 v202, 16, v164
	v_and_b32_e32 v203, 0xffff0000, v164
	v_lshlrev_b32_e32 v164, 16, v165
	v_and_b32_e32 v165, 0xffff0000, v165
	v_pk_fma_f32 v[126:127], v[126:127], 0.5, v[158:159] op_sel_hi:[1,0,1]
	v_pk_fma_f32 v[122:123], v[122:123], 0.5, v[160:161] op_sel_hi:[1,0,1]
	v_pk_fma_f32 v[118:119], v[118:119], 0.5, v[162:163] op_sel_hi:[1,0,1]
	v_pk_fma_f32 v[114:115], v[114:115], 0.5, v[164:165] op_sel_hi:[1,0,1]
	s_waitcnt vmcnt(12)
	v_lshlrev_b32_e32 v158, 16, v166
	v_and_b32_e32 v159, 0xffff0000, v166
	v_lshlrev_b32_e32 v160, 16, v167
	v_and_b32_e32 v161, 0xffff0000, v167
	v_lshlrev_b32_e32 v162, 16, v168
	v_and_b32_e32 v163, 0xffff0000, v168
	v_lshlrev_b32_e32 v164, 16, v169
	v_and_b32_e32 v165, 0xffff0000, v169
	v_lshlrev_b32_e32 v166, 16, v170
	v_and_b32_e32 v167, 0xffff0000, v170
	v_lshlrev_b32_e32 v168, 16, v171
	v_and_b32_e32 v169, 0xffff0000, v171
	v_lshlrev_b32_e32 v170, 16, v172
	v_and_b32_e32 v171, 0xffff0000, v172
	v_lshlrev_b32_e32 v172, 16, v173
	v_and_b32_e32 v173, 0xffff0000, v173
	v_pk_fma_f32 v[124:125], v[124:125], 0.5, v[196:197] op_sel_hi:[1,0,1]
	v_pk_fma_f32 v[110:111], v[110:111], 0.5, v[160:161] op_sel_hi:[1,0,1]
	v_pk_fma_f32 v[108:109], v[108:109], 0.5, v[158:159] op_sel_hi:[1,0,1]
	v_pk_fma_f32 v[104:105], v[104:105], 0.5, v[162:163] op_sel_hi:[1,0,1]
	v_pk_fma_f32 v[102:103], v[102:103], 0.5, v[168:169] op_sel_hi:[1,0,1]
	v_pk_fma_f32 v[100:101], v[100:101], 0.5, v[166:167] op_sel_hi:[1,0,1]
	v_pk_fma_f32 v[98:99], v[98:99], 0.5, v[172:173] op_sel_hi:[1,0,1]
	v_pk_fma_f32 v[96:97], v[96:97], 0.5, v[170:171] op_sel_hi:[1,0,1]
	v_pk_fma_f32 v[120:121], v[120:121], 0.5, v[198:199] op_sel_hi:[1,0,1]
	v_pk_fma_f32 v[116:117], v[116:117], 0.5, v[200:201] op_sel_hi:[1,0,1]
	v_pk_fma_f32 v[112:113], v[112:113], 0.5, v[202:203] op_sel_hi:[1,0,1]
	global_store_dwordx4 v[192:193], v[124:127], off
	global_store_dwordx4 v[192:193], v[120:123], off offset:16
	global_store_dwordx4 v[192:193], v[116:119], off offset:512
	global_store_dwordx4 v[192:193], v[112:115], off offset:528
	v_pk_fma_f32 v[106:107], v[106:107], 0.5, v[164:165] op_sel_hi:[1,0,1]
	global_store_dwordx4 v[194:195], v[108:111], off
	global_store_dwordx4 v[194:195], v[104:107], off offset:16
	global_store_dwordx4 v[194:195], v[100:103], off offset:512
	global_store_dwordx4 v[194:195], v[96:99], off offset:528
	s_waitcnt vmcnt(18)
	v_lshlrev_b32_e32 v104, 16, v177
	v_lshlrev_b32_e32 v100, 16, v175
	v_lshlrev_b64 v[96:97], 13, v[190:191]
	v_lshlrev_b32_e32 v98, 16, v174
	v_and_b32_e32 v99, 0xffff0000, v174
	v_and_b32_e32 v101, 0xffff0000, v175
	v_lshlrev_b32_e32 v102, 16, v176
	v_and_b32_e32 v103, 0xffff0000, v176
	v_and_b32_e32 v105, 0xffff0000, v177
	v_lshl_add_u64 v[96:97], v[144:145], 0, v[96:97]
	v_pk_fma_f32 v[94:95], v[94:95], 0.5, v[100:101] op_sel_hi:[1,0,1]
	v_pk_fma_f32 v[92:93], v[92:93], 0.5, v[98:99] op_sel_hi:[1,0,1]
	v_pk_fma_f32 v[90:91], v[90:91], 0.5, v[104:105] op_sel_hi:[1,0,1]
	v_pk_fma_f32 v[88:89], v[88:89], 0.5, v[102:103] op_sel_hi:[1,0,1]
	global_store_dwordx4 v[96:97], v[92:95], off
	global_store_dwordx4 v[96:97], v[88:91], off offset:16
	v_add_u32_e32 v98, 0x90, v148
	v_lshlrev_b32_e32 v92, 16, v180
	v_lshlrev_b32_e32 v88, 16, v178
	v_and_b32_e32 v89, 0xffff0000, v178
	v_lshlrev_b32_e32 v90, 16, v179
	v_and_b32_e32 v91, 0xffff0000, v179
	v_and_b32_e32 v93, 0xffff0000, v180
	v_lshlrev_b32_e32 v94, 16, v181
	v_and_b32_e32 v95, 0xffff0000, v181
	v_pk_fma_f32 v[86:87], v[86:87], 0.5, v[90:91] op_sel_hi:[1,0,1]
	v_pk_fma_f32 v[84:85], v[84:85], 0.5, v[88:89] op_sel_hi:[1,0,1]
	v_pk_fma_f32 v[76:77], v[76:77], 0.5, v[92:93] op_sel_hi:[1,0,1]
	v_pk_fma_f32 v[78:79], v[78:79], 0.5, v[94:95] op_sel_hi:[1,0,1]
	global_store_dwordx4 v[96:97], v[84:87], off offset:512
	global_store_dwordx4 v[96:97], v[76:79], off offset:528
	s_waitcnt vmcnt(20)
	v_lshlrev_b32_e32 v88, 16, v185
	v_lshlrev_b32_e32 v86, 16, v184
	v_lshlrev_b64 v[76:77], 13, v[150:151]
	v_lshl_add_u64 v[84:85], v[144:145], 0, v[76:77]
	v_lshlrev_b32_e32 v76, 16, v182
	v_and_b32_e32 v77, 0xffff0000, v182
	v_lshlrev_b32_e32 v78, 16, v183
	v_and_b32_e32 v79, 0xffff0000, v183
	v_and_b32_e32 v87, 0xffff0000, v184
	v_and_b32_e32 v89, 0xffff0000, v185
	v_pk_fma_f32 v[78:79], v[82:83], 0.5, v[78:79] op_sel_hi:[1,0,1]
	v_pk_fma_f32 v[76:77], v[80:81], 0.5, v[76:77] op_sel_hi:[1,0,1]
	v_pk_fma_f32 v[74:75], v[74:75], 0.5, v[88:89] op_sel_hi:[1,0,1]
	v_pk_fma_f32 v[72:73], v[72:73], 0.5, v[86:87] op_sel_hi:[1,0,1]
	global_store_dwordx4 v[84:85], v[76:79], off
	global_store_dwordx4 v[84:85], v[72:75], off offset:16
	v_add_u32_e32 v96, 0x80, v148
	v_lshlrev_b32_e32 v76, 16, v188
	v_lshlrev_b32_e32 v72, 16, v186
	v_and_b32_e32 v73, 0xffff0000, v186
	v_lshlrev_b32_e32 v74, 16, v187
	v_and_b32_e32 v75, 0xffff0000, v187
	v_and_b32_e32 v77, 0xffff0000, v188
	v_lshlrev_b32_e32 v78, 16, v189
	v_and_b32_e32 v79, 0xffff0000, v189
	v_pk_fma_f32 v[70:71], v[70:71], 0.5, v[74:75] op_sel_hi:[1,0,1]
	v_pk_fma_f32 v[68:69], v[68:69], 0.5, v[72:73] op_sel_hi:[1,0,1]
	v_pk_fma_f32 v[64:65], v[64:65], 0.5, v[76:77] op_sel_hi:[1,0,1]
	v_ashrrev_i32_e32 v97, 31, v96
	v_pk_fma_f32 v[66:67], v[66:67], 0.5, v[78:79] op_sel_hi:[1,0,1]
	global_store_dwordx4 v[84:85], v[68:71], off offset:512
	global_store_dwordx4 v[84:85], v[64:67], off offset:528
	v_ashrrev_i32_e32 v99, 31, v98
	v_add_u32_e32 v100, 0xa0, v148
	v_lshlrev_b64 v[64:65], 12, v[96:97]
	v_lshl_add_u64 v[64:65], v[146:147], 0, v[64:65]
	s_waitcnt vmcnt(16)
	v_mov_b64_e32 v[68:69], v[224:225]
	v_mov_b64_e32 v[70:71], v[226:227]
	v_mov_b64_e32 v[72:73], v[228:229]
	v_mov_b64_e32 v[74:75], v[230:231]
	v_lshlrev_b64 v[64:65], 12, v[98:99]
	v_lshl_add_u64 v[64:65], v[146:147], 0, v[64:65]
	v_mov_b64_e32 v[76:77], v[232:233]
	v_mov_b64_e32 v[78:79], v[234:235]
	v_mov_b64_e32 v[80:81], v[236:237]
	v_mov_b64_e32 v[82:83], v[238:239]
	v_ashrrev_i32_e32 v101, 31, v100
	v_lshlrev_b64 v[64:65], 12, v[100:101]
	v_lshl_add_u64 v[64:65], v[146:147], 0, v[64:65]
	v_mov_b64_e32 v[84:85], v[240:241]
	v_mov_b64_e32 v[86:87], v[242:243]
	v_mov_b64_e32 v[88:89], v[244:245]
	v_mov_b64_e32 v[90:91], v[246:247]
	v_add_u32_e32 v102, 0xb0, v148
	v_ashrrev_i32_e32 v103, 31, v102
	v_lshlrev_b64 v[64:65], 12, v[102:103]
	v_lshl_add_u64 v[64:65], v[146:147], 0, v[64:65]
	v_mov_b64_e32 v[92:93], v[248:249]
	v_mov_b64_e32 v[94:95], v[250:251]
	s_nop 0
	v_mov_b64_e32 v[64:65], v[204:205]
	v_mov_b64_e32 v[66:67], v[206:207]
	v_lshlrev_b64 v[96:97], 13, v[96:97]
	v_lshl_add_u64 v[96:97], v[144:145], 0, v[96:97]
	s_waitcnt lgkmcnt(0)
	v_lshlrev_b32_e32 v104, 16, v68
	v_and_b32_e32 v105, 0xffff0000, v68
	v_lshlrev_b32_e32 v68, 16, v69
	v_and_b32_e32 v69, 0xffff0000, v69
	v_lshlrev_b32_e32 v106, 16, v70
	v_and_b32_e32 v107, 0xffff0000, v70
	v_lshlrev_b32_e32 v70, 16, v71
	v_and_b32_e32 v71, 0xffff0000, v71
	v_pk_fma_f32 v[62:63], v[62:63], 0.5, v[68:69] op_sel_hi:[1,0,1]
	v_pk_fma_f32 v[60:61], v[60:61], 0.5, v[104:105] op_sel_hi:[1,0,1]
	v_pk_fma_f32 v[58:59], v[58:59], 0.5, v[70:71] op_sel_hi:[1,0,1]
	v_pk_fma_f32 v[56:57], v[56:57], 0.5, v[106:107] op_sel_hi:[1,0,1]
	global_store_dwordx4 v[96:97], v[60:63], off
	global_store_dwordx4 v[96:97], v[56:59], off offset:16
	s_nop 0
	v_lshlrev_b32_e32 v60, 16, v74
	v_lshlrev_b32_e32 v56, 16, v72
	v_and_b32_e32 v57, 0xffff0000, v72
	v_lshlrev_b32_e32 v58, 16, v73
	v_and_b32_e32 v59, 0xffff0000, v73
	v_and_b32_e32 v61, 0xffff0000, v74
	v_lshlrev_b32_e32 v62, 16, v75
	v_and_b32_e32 v63, 0xffff0000, v75
	v_pk_fma_f32 v[54:55], v[54:55], 0.5, v[58:59] op_sel_hi:[1,0,1]
	v_pk_fma_f32 v[52:53], v[52:53], 0.5, v[56:57] op_sel_hi:[1,0,1]
	v_pk_fma_f32 v[44:45], v[44:45], 0.5, v[60:61] op_sel_hi:[1,0,1]
	v_pk_fma_f32 v[46:47], v[46:47], 0.5, v[62:63] op_sel_hi:[1,0,1]
	global_store_dwordx4 v[96:97], v[52:55], off offset:512
	global_store_dwordx4 v[96:97], v[44:47], off offset:528
	v_lshlrev_b32_e32 v56, 16, v79
	v_lshlrev_b32_e32 v54, 16, v78
	v_lshlrev_b64 v[44:45], 13, v[98:99]
	v_lshl_add_u64 v[52:53], v[144:145], 0, v[44:45]
	v_lshlrev_b32_e32 v44, 16, v76
	v_and_b32_e32 v45, 0xffff0000, v76
	v_lshlrev_b32_e32 v46, 16, v77
	v_and_b32_e32 v47, 0xffff0000, v77
	v_and_b32_e32 v55, 0xffff0000, v78
	v_and_b32_e32 v57, 0xffff0000, v79
	v_pk_fma_f32 v[46:47], v[50:51], 0.5, v[46:47] op_sel_hi:[1,0,1]
	v_pk_fma_f32 v[44:45], v[48:49], 0.5, v[44:45] op_sel_hi:[1,0,1]
	v_pk_fma_f32 v[42:43], v[42:43], 0.5, v[56:57] op_sel_hi:[1,0,1]
	v_pk_fma_f32 v[40:41], v[40:41], 0.5, v[54:55] op_sel_hi:[1,0,1]
	global_store_dwordx4 v[52:53], v[44:47], off
	global_store_dwordx4 v[52:53], v[40:43], off offset:16
	s_nop 0
	v_lshlrev_b32_e32 v44, 16, v82
	v_lshlrev_b32_e32 v40, 16, v80
	v_and_b32_e32 v41, 0xffff0000, v80
	v_lshlrev_b32_e32 v42, 16, v81
	v_and_b32_e32 v43, 0xffff0000, v81
	v_and_b32_e32 v45, 0xffff0000, v82
	v_lshlrev_b32_e32 v46, 16, v83
	v_and_b32_e32 v47, 0xffff0000, v83
	v_pk_fma_f32 v[38:39], v[38:39], 0.5, v[42:43] op_sel_hi:[1,0,1]
	v_pk_fma_f32 v[36:37], v[36:37], 0.5, v[40:41] op_sel_hi:[1,0,1]
	v_pk_fma_f32 v[28:29], v[28:29], 0.5, v[44:45] op_sel_hi:[1,0,1]
	v_pk_fma_f32 v[30:31], v[30:31], 0.5, v[46:47] op_sel_hi:[1,0,1]
	global_store_dwordx4 v[52:53], v[36:39], off offset:512
	global_store_dwordx4 v[52:53], v[28:31], off offset:528
	v_lshlrev_b32_e32 v40, 16, v87
	v_lshlrev_b32_e32 v38, 16, v86
	v_lshlrev_b64 v[28:29], 13, v[100:101]
	v_lshl_add_u64 v[36:37], v[144:145], 0, v[28:29]
	v_lshlrev_b32_e32 v28, 16, v84
	v_and_b32_e32 v29, 0xffff0000, v84
	v_lshlrev_b32_e32 v30, 16, v85
	v_and_b32_e32 v31, 0xffff0000, v85
	v_and_b32_e32 v39, 0xffff0000, v86
	v_and_b32_e32 v41, 0xffff0000, v87
	v_pk_fma_f32 v[30:31], v[34:35], 0.5, v[30:31] op_sel_hi:[1,0,1]
	v_pk_fma_f32 v[28:29], v[32:33], 0.5, v[28:29] op_sel_hi:[1,0,1]
	v_pk_fma_f32 v[26:27], v[26:27], 0.5, v[40:41] op_sel_hi:[1,0,1]
	v_pk_fma_f32 v[24:25], v[24:25], 0.5, v[38:39] op_sel_hi:[1,0,1]
	global_store_dwordx4 v[36:37], v[28:31], off
	global_store_dwordx4 v[36:37], v[24:27], off offset:16
	s_nop 0
	v_lshlrev_b32_e32 v28, 16, v90
	v_lshlrev_b32_e32 v24, 16, v88
	v_and_b32_e32 v25, 0xffff0000, v88
	v_lshlrev_b32_e32 v26, 16, v89
	v_and_b32_e32 v27, 0xffff0000, v89
	v_and_b32_e32 v29, 0xffff0000, v90
	v_lshlrev_b32_e32 v30, 16, v91
	v_and_b32_e32 v31, 0xffff0000, v91
	v_pk_fma_f32 v[22:23], v[22:23], 0.5, v[26:27] op_sel_hi:[1,0,1]
	v_pk_fma_f32 v[20:21], v[20:21], 0.5, v[24:25] op_sel_hi:[1,0,1]
	v_pk_fma_f32 v[12:13], v[12:13], 0.5, v[28:29] op_sel_hi:[1,0,1]
	v_pk_fma_f32 v[14:15], v[14:15], 0.5, v[30:31] op_sel_hi:[1,0,1]
	global_store_dwordx4 v[36:37], v[20:23], off offset:512
	global_store_dwordx4 v[36:37], v[12:15], off offset:528
	v_lshlrev_b32_e32 v24, 16, v95
	v_lshlrev_b32_e32 v22, 16, v94
	v_lshlrev_b64 v[12:13], 13, v[102:103]
	v_lshl_add_u64 v[20:21], v[144:145], 0, v[12:13]
	v_lshlrev_b32_e32 v12, 16, v92
	v_and_b32_e32 v13, 0xffff0000, v92
	v_lshlrev_b32_e32 v14, 16, v93
	v_and_b32_e32 v15, 0xffff0000, v93
	v_and_b32_e32 v23, 0xffff0000, v94
	v_and_b32_e32 v25, 0xffff0000, v95
	v_pk_fma_f32 v[14:15], v[18:19], 0.5, v[14:15] op_sel_hi:[1,0,1]
	v_pk_fma_f32 v[12:13], v[16:17], 0.5, v[12:13] op_sel_hi:[1,0,1]
	v_pk_fma_f32 v[10:11], v[10:11], 0.5, v[24:25] op_sel_hi:[1,0,1]
	v_pk_fma_f32 v[8:9], v[8:9], 0.5, v[22:23] op_sel_hi:[1,0,1]
	global_store_dwordx4 v[20:21], v[12:15], off
	global_store_dwordx4 v[20:21], v[8:11], off offset:16
	s_nop 0
	v_lshlrev_b32_e32 v12, 16, v66
	v_lshlrev_b32_e32 v8, 16, v64
	v_and_b32_e32 v9, 0xffff0000, v64
	v_lshlrev_b32_e32 v10, 16, v65
	v_and_b32_e32 v11, 0xffff0000, v65
	v_and_b32_e32 v13, 0xffff0000, v66
	v_lshlrev_b32_e32 v14, 16, v67
	v_and_b32_e32 v15, 0xffff0000, v67
	v_pk_fma_f32 v[6:7], v[6:7], 0.5, v[10:11] op_sel_hi:[1,0,1]
	v_pk_fma_f32 v[4:5], v[4:5], 0.5, v[8:9] op_sel_hi:[1,0,1]
	v_pk_fma_f32 v[2:3], v[2:3], 0.5, v[14:15] op_sel_hi:[1,0,1]
	v_pk_fma_f32 v[0:1], v[0:1], 0.5, v[12:13] op_sel_hi:[1,0,1]
	global_store_dwordx4 v[20:21], v[4:7], off offset:512
	global_store_dwordx4 v[20:21], v[0:3], off offset:528
	s_cbranch_vccnz .LBB0_1472
	s_and_b64 vcc, exec, s[60:61]
	s_cbranch_vccnz .LBB0_1471
	s_barrier
	s_branch .LBB0_1471
